# S5 backward scan: the six regular steps per iteration rewritten from dependent packed-f32 ops + hazard nops to plain f32 mul/fma/add with identical rounding
# baseline (speedup 1.0000x reference)
; __device__ __forceinline__ bf16_t f2bf(float f) { unsigned u = __float_as_uint(f); return (bf16_t)((u + 0x7fffu + ((u >> 16) & 1u)) >> 16); }
; #define S5_STEP(r) do { const float sr = sl[(r) * 256], si = sl[(r) * 256 + 64]; const float nr = lr * xr - li * xi + sr, ni = lr * xi + li * xr + si; xr = nr; xi = ni; } while (0)
; __device__ __forceinline__ void ph_s5_out(unsigned char* lds_, const bf16_t* Z, const bf16_t* TZB, const bf16_t* CQ, const float2* LP, const float* SLOC, const float* lamT, bf16_t* YG, int nrct, int u0, int ustep) { PH_IDS;
;     ...
;             if (lat) {
;                 if (d == 0) { for (int r = 0; r < 4 + c0; ++r) S5_STEP(r);
;                     for (int r = 0; r < 16; ++r) { xp[r * 256] = f2bf(xr); xp[r * 256 + 64] = f2bf(xi); S5_STEP(4 + c0 + r); } }
;                 else { for (int r = 3; r >= 0; --r) S5_STEP(r);
;                     for (int c = 31; c >= c0 + 16; --c) S5_STEP(4 + c);
;                     for (int r = 15; r >= 0; --r) { xp[r * 256] = f2bf(xr); xp[r * 256 + 64] = f2bf(xi); S5_STEP(4 + c0 + r); } }
.LBB0_861:
	v_pk_mul_f32 v[14:15], v[6:7], v[12:13] op_sel_hi:[1,0]
	ds_read2st64_b32 v[12:13], v11 offset0:28 offset1:29
	ds_read2st64_b32 v[18:19], v11 offset0:24 offset1:25
	ds_read2st64_b32 v[20:21], v11 offset0:20 offset1:21
	ds_read2st64_b32 v[22:23], v11 offset0:16 offset1:17
	ds_read2st64_b32 v[24:25], v11 offset0:12 offset1:13
	ds_read2st64_b32 v[26:27], v11 offset0:8 offset1:9
	ds_read2st64_b32 v[28:29], v11 offset0:4 offset1:5
	ds_read2st64_b32 v[30:31], v11 offset1:1
	v_add_u32_e32 v11, 0xffffe000, v11
	v_pk_fma_f32 v[32:33], v[8:9], v[10:11], v[14:15]
	v_pk_fma_f32 v[14:15], v[8:9], v[10:11], v[14:15] op_sel_hi:[1,0,1] neg_lo:[0,0,1] neg_hi:[0,0,1]
	s_add_i32 s15, s15, -8
	v_mov_b32_e32 v33, v15
	s_waitcnt lgkmcnt(7)
	v_mov_b32_e32 v14, v13
	v_mov_b32_e32 v15, v12
	v_pk_add_f32 v[14:15], v[32:33], v[14:15]
	s_waitcnt lgkmcnt(6)
	v_mov_b32_e32 v12, v19
	v_mov_b32_e32 v13, v18
	s_waitcnt lgkmcnt(5)
	v_mov_b32_e32 v18, v21
	v_mov_b32_e32 v19, v20
	s_waitcnt lgkmcnt(4)
	v_mov_b32_e32 v20, v23
	v_mov_b32_e32 v21, v22
	s_waitcnt lgkmcnt(3)
	v_mov_b32_e32 v22, v25
	v_mov_b32_e32 v23, v24
	s_waitcnt lgkmcnt(2)
	v_mov_b32_e32 v24, v27
	v_mov_b32_e32 v25, v26
	s_waitcnt lgkmcnt(1)
	v_mov_b32_e32 v26, v29
	v_mov_b32_e32 v27, v28
	s_waitcnt lgkmcnt(0)
	v_mov_b32_e32 v28, v31
	v_mov_b32_e32 v29, v30
	v_pk_mul_f32 v[30:31], v[6:7], v[14:15] op_sel_hi:[1,0]
	s_cmp_le_u32 s15, s14
	v_pk_fma_f32 v[32:33], v[8:9], v[14:15], v[30:31] op_sel:[0,1,0]
	v_pk_fma_f32 v[14:15], v[8:9], v[14:15], v[30:31] op_sel:[0,1,0] neg_lo:[0,0,1] neg_hi:[0,0,1]
	s_nop 0
	v_mov_b32_e32 v33, v15
	v_pk_add_f32 v[12:13], v[32:33], v[12:13]
	s_nop 0
	v_mul_f32_e32 v14, v6, v12
	v_mul_f32_e32 v15, v7, v12
	v_fma_f32 v14, v8, v13, v14
	v_fma_f32 v15, v9, v13, -v15
	v_add_f32_e32 v12, v14, v18
	v_add_f32_e32 v13, v15, v19
	v_mul_f32_e32 v14, v6, v12
	v_mul_f32_e32 v15, v7, v12
	v_fma_f32 v14, v8, v13, v14
	v_fma_f32 v15, v9, v13, -v15
	v_add_f32_e32 v12, v14, v20
	v_add_f32_e32 v13, v15, v21
	v_mul_f32_e32 v14, v6, v12
	v_mul_f32_e32 v15, v7, v12
	v_fma_f32 v14, v8, v13, v14
	v_fma_f32 v15, v9, v13, -v15
	v_add_f32_e32 v12, v14, v22
	v_add_f32_e32 v13, v15, v23
	v_mul_f32_e32 v14, v6, v12
	v_mul_f32_e32 v15, v7, v12
	v_fma_f32 v14, v8, v13, v14
	v_fma_f32 v15, v9, v13, -v15
	v_add_f32_e32 v12, v14, v24
	v_add_f32_e32 v13, v15, v25
	v_mul_f32_e32 v14, v6, v12
	v_mul_f32_e32 v15, v7, v12
	v_fma_f32 v14, v8, v13, v14
	v_fma_f32 v15, v9, v13, -v15
	v_add_f32_e32 v12, v14, v26
	v_add_f32_e32 v13, v15, v27
	v_mul_f32_e32 v14, v6, v12
	v_mul_f32_e32 v15, v7, v12
	v_fma_f32 v14, v8, v13, v14
	v_fma_f32 v15, v9, v13, -v15
	v_add_f32_e32 v12, v14, v28
	v_add_f32_e32 v13, v15, v29
	v_mov_b32_e32 v10, v13
	s_cbranch_scc0 .LBB0_861
